# plus cmp_bias_jobs inner loop: 32 loads in flight per batch instead of serialized load pair per k
# speedup vs baseline: 1.1461x; 1.0041x over previous
; DI void cmp_bias_jobs(const Params& p) {
;     ...
;   for (int it = (int)gridDim.x - 1 - (int)blockIdx.x; it < 32; it += gridDim.x) {
;     const int job = it >> 3, cg8 = it & 7, l = job >> 1, kv = job & 1;
;     const float* pe = p.in[kv ? 20 : 17] + (size_t)l * 4096;
;     const float* w1 = p.in[kv ? 21 : 18] + (size_t)l * 4096 * 256;
;     const int c = cg8 * 32 + cl;
;     float s = 0.f;
; #pragma unroll 8
;     for (int k = part * 256; k < part * 256 + 256; ++k) s += pe[k] * w1[(size_t)k * 256 + c];
;     red[part * 32 + cl] = s;
;     __syncthreads();
;     if (tid < 32) { float a = 0.f; for (int q = 0; q < 16; ++q) a += red[q * 32 + tid]; ((float*)(p.ws + A_BIAS1))[job * 256 + cg8 * 32 + tid] = a; }
;     __syncthreads();
;   }
.LBB0_2657:
	s_mov_b64 s[0:1], 0x2000
	s_movk_i32 s6, 16
.Lcb_loop:
	global_load_dword v20, v[8:9], off offset:-28
	global_load_dword v21, v[8:9], off offset:-24
	global_load_dword v22, v[8:9], off offset:-20
	global_load_dword v23, v[8:9], off offset:-16
	global_load_dword v24, v[8:9], off offset:-12
	global_load_dword v25, v[8:9], off offset:-8
	global_load_dword v26, v[8:9], off offset:-4
	global_load_dword v27, v[8:9], off
	global_load_dword v28, v[6:7], off offset:-4096
	global_load_dword v29, v[6:7], off offset:-3072
	global_load_dword v30, v[6:7], off offset:-2048
	global_load_dword v31, v[6:7], off offset:-1024
	global_load_dword v32, v[6:7], off
	global_load_dword v33, v[6:7], off offset:1024
	global_load_dword v34, v[6:7], off offset:2048
	global_load_dword v35, v[6:7], off offset:3072
	v_lshl_add_u64 v[6:7], v[6:7], 0, s[0:1]
	v_lshl_add_u64 v[8:9], v[8:9], 0, 32
	global_load_dword v36, v[8:9], off offset:-28
	global_load_dword v37, v[8:9], off offset:-24
	global_load_dword v38, v[8:9], off offset:-20
	global_load_dword v39, v[8:9], off offset:-16
	global_load_dword v40, v[8:9], off offset:-12
	global_load_dword v41, v[8:9], off offset:-8
	global_load_dword v42, v[8:9], off offset:-4
	global_load_dword v43, v[8:9], off
	global_load_dword v44, v[6:7], off offset:-4096
	global_load_dword v45, v[6:7], off offset:-3072
	global_load_dword v46, v[6:7], off offset:-2048
	global_load_dword v47, v[6:7], off offset:-1024
	global_load_dword v48, v[6:7], off
	global_load_dword v49, v[6:7], off offset:1024
	global_load_dword v50, v[6:7], off offset:2048
	global_load_dword v51, v[6:7], off offset:3072
	v_lshl_add_u64 v[6:7], v[6:7], 0, s[0:1]
	v_lshl_add_u64 v[8:9], v[8:9], 0, 32
	s_waitcnt vmcnt(16)
	v_fmac_f32_e32 v14, v20, v28
	v_fmac_f32_e32 v14, v21, v29
	v_fmac_f32_e32 v14, v22, v30
	v_fmac_f32_e32 v14, v23, v31
	v_fmac_f32_e32 v14, v24, v32
	v_fmac_f32_e32 v14, v25, v33
	v_fmac_f32_e32 v14, v26, v34
	v_fmac_f32_e32 v14, v27, v35
	s_waitcnt vmcnt(0)
	v_fmac_f32_e32 v14, v36, v44
	v_fmac_f32_e32 v14, v37, v45
	v_fmac_f32_e32 v14, v38, v46
	v_fmac_f32_e32 v14, v39, v47
	v_fmac_f32_e32 v14, v40, v48
	v_fmac_f32_e32 v14, v41, v49
	v_fmac_f32_e32 v14, v42, v50
	v_fmac_f32_e32 v14, v43, v51
	s_add_i32 s6, s6, -1
	s_cmp_lg_u32 s6, 0
	s_cbranch_scc1 .Lcb_loop
	ds_write_b32 v11, v14
	s_waitcnt lgkmcnt(0)
	s_barrier
	s_and_saveexec_b64 s[0:1], vcc
	s_cbranch_execz .LBB0_2648
	ds_read2_b32 v[6:7], v11 offset1:32
	ds_read2_b32 v[8:9], v11 offset0:64 offset1:96
	ds_read2_b32 v[14:15], v11 offset0:128 offset1:160
	ds_read2_b32 v[16:17], v11 offset0:192 offset1:224
	v_add_u32_e32 v18, 0x400, v11
	s_waitcnt lgkmcnt(3)
	v_add_f32_e32 v6, 0, v6
	v_add_f32_e32 v6, v6, v7
	s_waitcnt lgkmcnt(2)
	v_add_f32_e32 v6, v6, v8
	v_add_f32_e32 v6, v6, v9
	s_waitcnt lgkmcnt(1)
	v_add_f32_e32 v8, v6, v14
	ds_read2_b32 v[6:7], v18 offset1:32
	v_add_f32_e32 v8, v8, v15
	s_waitcnt lgkmcnt(1)
	v_add_f32_e32 v8, v8, v16
	v_add_f32_e32 v14, v8, v17
	ds_read2_b32 v[8:9], v18 offset0:64 offset1:96
	s_waitcnt lgkmcnt(1)
	v_add_f32_e32 v6, v14, v6
	ds_read2_b32 v[14:15], v18 offset0:128 offset1:160
	v_add_f32_e32 v16, v6, v7
	ds_read2_b32 v[6:7], v18 offset0:192 offset1:224
	s_waitcnt lgkmcnt(2)
	v_add_f32_e32 v8, v16, v8
	v_add_f32_e32 v8, v8, v9
	s_waitcnt lgkmcnt(1)
	v_add_f32_e32 v8, v8, v14
	v_add_f32_e32 v8, v8, v15
	s_waitcnt lgkmcnt(0)
	v_add_f32_e32 v6, v8, v6
	v_add_f32_e32 v8, v6, v7
	v_lshl_add_u32 v6, s25, 5, v0
	v_ashrrev_i32_e32 v7, 31, v6
	v_lshl_add_u64 v[6:7], v[6:7], 2, s[2:3]
	global_store_dword v[6:7], v8, off
	s_branch .LBB0_2648
